# modnorm prologue: forget-weight staging loop unrolled (16 loads issued together behind counted waits instead of 4 serialized round trips)
# baseline (speedup 1.0000x reference)
.LBB0_298:
	s_movk_i32 s4, 0x50
	v_bitop3_b32 v26, v3, s4, v239 bitop3:0x6c
	s_movk_i32 s4, 0x60
	v_bitop3_b32 v27, v3, s4, v239 bitop3:0x6c
	s_movk_i32 s4, 0x70
	v_bitop3_b32 v28, v3, s4, v239 bitop3:0x6c
	s_movk_i32 s4, 0x80
	v_bitop3_b32 v29, v3, s4, v239 bitop3:0x6c
	s_movk_i32 s4, 0x90
	v_bitop3_b32 v30, v3, s4, v239 bitop3:0x6c
	s_movk_i32 s4, 0xa0
	v_bitop3_b32 v31, v3, s4, v239 bitop3:0x6c
	s_movk_i32 s4, 0xb0
	v_bitop3_b32 v32, v3, s4, v239 bitop3:0x6c
	s_movk_i32 s4, 0xc0
	v_bitop3_b32 v33, v3, s4, v239 bitop3:0x6c
	s_movk_i32 s4, 0xd0
	v_bitop3_b32 v34, v3, s4, v239 bitop3:0x6c
	s_movk_i32 s4, 0xe0
	v_bitop3_b32 v35, v3, s4, v239 bitop3:0x6c
	s_movk_i32 s4, 0xf0
	v_bitop3_b32 v36, v3, s4, v239 bitop3:0x6c
	v_and_b32_e32 v20, 14, v3
	v_and_b32_e32 v21, 0xff0, v3
	s_add_i32 s6, 0, 0x10000
	s_add_i32 s7, 0, 0x12000
	v_bitop3_b32 v22, v3, 16, v239 bitop3:0x6c
	v_bitop3_b32 v23, v3, 32, v239 bitop3:0x6c
	v_bitop3_b32 v24, v3, 48, v239 bitop3:0x6c
	v_bitop3_b32 v25, v3, 64, v239 bitop3:0x6c
	v_add3_u32 v21, 0, v21, v20
	v_add3_u32 v22, 0, v22, v20
	v_add3_u32 v23, 0, v23, v20
	v_add3_u32 v24, 0, v24, v20
	v_add3_u32 v25, 0, v25, v20
	v_add3_u32 v26, 0, v26, v20
	v_add3_u32 v27, 0, v27, v20
	v_add3_u32 v28, 0, v28, v20
	v_add3_u32 v29, 0, v29, v20
	v_add3_u32 v30, 0, v30, v20
	v_add3_u32 v31, 0, v31, v20
	v_add3_u32 v32, 0, v32, v20
	v_add3_u32 v33, s6, v33, v20
	v_add3_u32 v34, s8, v34, v20
	v_add3_u32 v35, s7, v35, v20
	v_add3_u32 v20, s9, v36, v20
	s_mov_b64 s[4:5], 0xe08000
	global_load_dwordx4 v[4:7], v[0:1], off
	global_load_dwordx4 v[8:11], v[0:1], off offset:16
	global_load_dwordx4 v[12:15], v[0:1], off offset:32
	global_load_dwordx4 v[16:19], v[0:1], off offset:48
	v_lshl_add_u64 v[0:1], v[0:1], 0, s[4:5]
	global_load_dwordx4 v[72:75], v[0:1], off
	global_load_dwordx4 v[76:79], v[0:1], off offset:16
	global_load_dwordx4 v[80:83], v[0:1], off offset:32
	global_load_dwordx4 v[84:87], v[0:1], off offset:48
	v_lshl_add_u64 v[0:1], v[0:1], 0, s[4:5]
	global_load_dwordx4 v[88:91], v[0:1], off
	global_load_dwordx4 v[92:95], v[0:1], off offset:16
	global_load_dwordx4 v[96:99], v[0:1], off offset:32
	global_load_dwordx4 v[100:103], v[0:1], off offset:48
	v_lshl_add_u64 v[0:1], v[0:1], 0, s[4:5]
	global_load_dwordx4 v[104:107], v[0:1], off
	global_load_dwordx4 v[108:111], v[0:1], off offset:16
	global_load_dwordx4 v[112:115], v[0:1], off offset:32
	global_load_dwordx4 v[116:119], v[0:1], off offset:48
	v_lshl_add_u64 v[0:1], v[0:1], 0, s[4:5]
	s_waitcnt vmcnt(12)
	v_cvt_pk_bf16_f32 v4, v4, s0
	v_cvt_pk_bf16_f32 v5, v5, s0
	v_cvt_pk_bf16_f32 v6, v6, s0
	v_cvt_pk_bf16_f32 v7, v7, s0
	v_cvt_pk_bf16_f32 v8, v8, s0
	v_cvt_pk_bf16_f32 v9, v9, s0
	v_cvt_pk_bf16_f32 v10, v10, s0
	v_cvt_pk_bf16_f32 v11, v11, s0
	v_cvt_pk_bf16_f32 v12, v12, s0
	v_cvt_pk_bf16_f32 v13, v13, s0
	v_cvt_pk_bf16_f32 v14, v14, s0
	v_cvt_pk_bf16_f32 v15, v15, s0
	v_cvt_pk_bf16_f32 v16, v16, s0
	v_cvt_pk_bf16_f32 v17, v17, s0
	v_cvt_pk_bf16_f32 v18, v18, s0
	v_cvt_pk_bf16_f32 v19, v19, s0
	ds_write_b16 v21, v4 offset:16384
	ds_write_b16 v22, v5 offset:20480
	ds_write_b16 v23, v6 offset:24576
	ds_write_b16 v24, v7 offset:28672
	ds_write_b16 v25, v8 offset:32768
	ds_write_b16 v26, v9 offset:36864
	ds_write_b16 v27, v10 offset:40960
	ds_write_b16 v28, v11 offset:45056
	ds_write_b16 v29, v12 offset:49152
	ds_write_b16 v30, v13 offset:53248
	ds_write_b16 v31, v14 offset:57344
	ds_write_b16 v32, v15 offset:61440
	ds_write_b16 v33, v16
	ds_write_b16 v34, v17
	ds_write_b16 v35, v18
	ds_write_b16 v20, v19
	s_waitcnt vmcnt(8)
	v_cvt_pk_bf16_f32 v72, v72, s0
	v_cvt_pk_bf16_f32 v73, v73, s0
	v_cvt_pk_bf16_f32 v74, v74, s0
	v_cvt_pk_bf16_f32 v75, v75, s0
	v_cvt_pk_bf16_f32 v76, v76, s0
	v_cvt_pk_bf16_f32 v77, v77, s0
	v_cvt_pk_bf16_f32 v78, v78, s0
	v_cvt_pk_bf16_f32 v79, v79, s0
	v_cvt_pk_bf16_f32 v80, v80, s0
	v_cvt_pk_bf16_f32 v81, v81, s0
	v_cvt_pk_bf16_f32 v82, v82, s0
	v_cvt_pk_bf16_f32 v83, v83, s0
	v_cvt_pk_bf16_f32 v84, v84, s0
	v_cvt_pk_bf16_f32 v85, v85, s0
	v_cvt_pk_bf16_f32 v86, v86, s0
	v_cvt_pk_bf16_f32 v87, v87, s0
	ds_write_b16 v21, v72 offset:17408
	ds_write_b16 v22, v73 offset:21504
	ds_write_b16 v23, v74 offset:25600
	ds_write_b16 v24, v75 offset:29696
	ds_write_b16 v25, v76 offset:33792
	ds_write_b16 v26, v77 offset:37888
	ds_write_b16 v27, v78 offset:41984
	ds_write_b16 v28, v79 offset:46080
	ds_write_b16 v29, v80 offset:50176
	ds_write_b16 v30, v81 offset:54272
	ds_write_b16 v31, v82 offset:58368
	ds_write_b16 v32, v83 offset:62464
	ds_write_b16 v33, v84 offset:1024
	ds_write_b16 v34, v85 offset:1024
	ds_write_b16 v35, v86 offset:1024
	ds_write_b16 v20, v87 offset:1024
	s_waitcnt vmcnt(4)
	v_cvt_pk_bf16_f32 v88, v88, s0
	v_cvt_pk_bf16_f32 v89, v89, s0
	v_cvt_pk_bf16_f32 v90, v90, s0
	v_cvt_pk_bf16_f32 v91, v91, s0
	v_cvt_pk_bf16_f32 v92, v92, s0
	v_cvt_pk_bf16_f32 v93, v93, s0
	v_cvt_pk_bf16_f32 v94, v94, s0
	v_cvt_pk_bf16_f32 v95, v95, s0
	v_cvt_pk_bf16_f32 v96, v96, s0
	v_cvt_pk_bf16_f32 v97, v97, s0
	v_cvt_pk_bf16_f32 v98, v98, s0
	v_cvt_pk_bf16_f32 v99, v99, s0
	v_cvt_pk_bf16_f32 v100, v100, s0
	v_cvt_pk_bf16_f32 v101, v101, s0
	v_cvt_pk_bf16_f32 v102, v102, s0
	v_cvt_pk_bf16_f32 v103, v103, s0
	ds_write_b16 v21, v88 offset:18432
	ds_write_b16 v22, v89 offset:22528
	ds_write_b16 v23, v90 offset:26624
	ds_write_b16 v24, v91 offset:30720
	ds_write_b16 v25, v92 offset:34816
	ds_write_b16 v26, v93 offset:38912
	ds_write_b16 v27, v94 offset:43008
	ds_write_b16 v28, v95 offset:47104
	ds_write_b16 v29, v96 offset:51200
	ds_write_b16 v30, v97 offset:55296
	ds_write_b16 v31, v98 offset:59392
	ds_write_b16 v32, v99 offset:63488
	ds_write_b16 v33, v100 offset:2048
	ds_write_b16 v34, v101 offset:2048
	ds_write_b16 v35, v102 offset:2048
	ds_write_b16 v20, v103 offset:2048
	s_waitcnt vmcnt(0)
	v_cvt_pk_bf16_f32 v104, v104, s0
	v_cvt_pk_bf16_f32 v105, v105, s0
	v_cvt_pk_bf16_f32 v106, v106, s0
	v_cvt_pk_bf16_f32 v107, v107, s0
	v_cvt_pk_bf16_f32 v108, v108, s0
	v_cvt_pk_bf16_f32 v109, v109, s0
	v_cvt_pk_bf16_f32 v110, v110, s0
	v_cvt_pk_bf16_f32 v111, v111, s0
	v_cvt_pk_bf16_f32 v112, v112, s0
	v_cvt_pk_bf16_f32 v113, v113, s0
	v_cvt_pk_bf16_f32 v114, v114, s0
	v_cvt_pk_bf16_f32 v115, v115, s0
	v_cvt_pk_bf16_f32 v116, v116, s0
	v_cvt_pk_bf16_f32 v117, v117, s0
	v_cvt_pk_bf16_f32 v118, v118, s0
	v_cvt_pk_bf16_f32 v119, v119, s0
	ds_write_b16 v21, v104 offset:19456
	ds_write_b16 v22, v105 offset:23552
	ds_write_b16 v23, v106 offset:27648
	ds_write_b16 v24, v107 offset:31744
	ds_write_b16 v25, v108 offset:35840
	ds_write_b16 v26, v109 offset:39936
	ds_write_b16 v27, v110 offset:44032
	ds_write_b16 v28, v111 offset:48128
	ds_write_b16 v29, v112 offset:52224
	ds_write_b16 v30, v113 offset:56320
	ds_write_b16 v31, v114 offset:60416
	ds_write_b16 v32, v115 offset:64512
	ds_write_b16 v33, v116 offset:3072
	ds_write_b16 v34, v117 offset:3072
	ds_write_b16 v35, v118 offset:3072
	ds_write_b16 v20, v119 offset:3072
	v_add_u32_e32 v2, 0x800, v2
	v_add_u32_e32 v3, 0x1000, v3
